# diff steady bodies unrolled x2 by interval parity: all LDS addresses immediates (no per-interval address VALU/SALU), precomputed end bound
# speedup vs baseline: 1.0193x; 1.0020x over previous
; #define LAS __attribute__((address_space(3)))
; template <bool DIFF>
; __device__ __forceinline__ void attn_unit(const AttnP& A, int b, int h, int qi, ldsp lds) {
;     ...
;     const int tid = tid_, lane = tid & 63, w = __builtin_amdgcn_readfirstlane(tid >> 6), r32 = lane & 31, hi = lane >> 5;
;     const int comp = DIFF ? (w >> 2) : 0, wq = DIFF ? (w & 3) : w;
;     const int qstart = qi == 0 ? 0 : 64 + QROWS * (qi - 1);
;     const int nt = qi == 0 ? 1 : 1 + TPQ * qi;
;     const int diag0 = qi == 0 ? 0 : nt - TPQ;
;     const int q_pp = qstart + 32 * wq + r32, qmax_w = qstart + 32 * wq + 31;
;     const bool store_ok = (qi != 0) || (b == 0 && q_pp >= 48 && q_pp < 64);
;     const size_t Rb = (size_t)b * LP;
;     const int qcol = DIFF ? h * 128 + comp * 64 : 2048 + h * 64;
;     const int kcol = DIFF ? 512 + h * 128 : 2560 + h * 64;
;     const int vcol = DIFF ? 1024 + h * 128 : 3072 + h * 64;
;     const int zcol = DIFF ? 1536 + h * 128 : 3584 + h * 64;
;     const int mcol = DIFF ? h * 128 : 512 + h * 64;
;     const bf16* Pq = A.P + (Rb + q_pp) * NP;
;     bf16x8 qf[4];
; #pragma unroll
;     for (int c = 0; c < 4; ++c) qf[c] = *(const bf16x8*)(Pq + qcol + 16 * c + 8 * hi);
;     LAS float* pref = (LAS float*)(lds + LDS_PREF);
;     u32x4 kreg[NPIECE], vreg[NPIECE]; float clreg = 0.f;
;     ...
;     LOAD_TILE(kt0);
;     STORE_TILE(kt0 & 1);
;     __syncthreads();
;     float cq = 0.f;
;     if (!DIFF) cq = pref[q_pp >> 6] + A.cumloc[(Rb + q_pp) * 8 + h];
;     float mhat = 0.f, l_run = 0.f;
;     f32x16 negm;
; #pragma unroll
;     for (int r = 0; r < 16; ++r) negm[r] = 0.f;
;     f32x16 o[NTD];
; #pragma unroll
;     for (int t = 0; t < NTD; ++t)
; #pragma unroll
;         for (int r = 0; r < 16; ++r) o[t][r] = 0.f;
;     const int trb = (4 * hi + ((lane & 15) >> 2)) * VP + ((lane >> 4) & 1) * 32 + (lane & 3) * 8;
.LBB0_495:
	s_and_b64 vcc, exec, s[0:1]
	s_cbranch_vccz .LBB0_439
	s_mul_hi_i32 s0, s31, 0x7e07e07f
	s_lshr_b32 s1, s0, 31
	s_ashr_i32 s51, s0, 5
	s_add_i32 s51, s51, s1
	v_mov_b32_e32 v225, v200
	s_mul_i32 s0, s51, 0x41
	s_sub_i32 s0, s31, s0
	v_readfirstlane_b32 s64, v225
	s_ashr_i32 s22, s51, 2
	s_ashr_i32 s70, s64, 8
	s_bfe_u32 s65, s64, 0x20006
	s_cmp_eq_u32 s0, 0
	s_cselect_b64 s[24:25], -1, 0
	s_lshl_b32 s1, s0, 7
	s_sub_i32 s1, s1, 64
	s_cmp_lg_u32 s0, 0
	s_cselect_b64 s[16:17], -1, 0
	s_and_b64 s[40:41], s[16:17], exec
	s_cselect_b32 s1, s1, 0
	s_lshl_b32 s23, s65, 5
	v_and_b32_e32 v6, 31, v225
	s_add_i32 s1, s23, s1
	v_or_b32_e32 v192, s1, v6
	s_lshl_b32 s23, s51, 7
	v_ashrrev_i32_e32 v193, 31, v192
	s_and_b32 s50, s23, 0x180
	s_lshl_b32 s23, s70, 6
	v_mad_i64_i32 v[2:3], s[44:45], s22, v221, v[192:193]
	s_add_i32 s40, s23, s50
	v_lshlrev_b64 v[2:3], 13, v[2:3]
	v_bfe_u32 v7, v225, 5, 1
	v_lshl_add_u64 v[190:191], s[58:59], 0, v[2:3]
	s_ashr_i32 s41, s40, 31
	v_lshl_add_u64 v[2:3], s[40:41], 1, v[190:191]
	v_lshlrev_b32_e32 v194, 4, v7
	v_mov_b32_e32 v195, v1
	s_mul_i32 s41, s22, 0x4080000
	v_ashrrev_i32_e32 v8, 4, v225
	v_lshl_add_u64 v[2:3], v[2:3], 0, v[194:195]
	s_mul_hi_i32 s40, s22, 0x4080000
	s_add_u32 s44, s58, s41
	v_ashrrev_i32_e32 v9, 31, v8
	global_load_dwordx4 v[116:119], v[2:3], off
	global_load_dwordx4 v[120:123], v[2:3], off offset:32
	global_load_dwordx4 v[124:127], v[2:3], off offset:64
	global_load_dwordx4 v[128:131], v[2:3], off offset:96
	s_addc_u32 s45, s59, s40
	v_lshlrev_b64 v[2:3], 13, v[8:9]
	v_lshl_add_u64 v[4:5], s[44:45], 0, v[2:3]
	s_lshl_b32 s34, s50, 1
	v_lshlrev_b32_e32 v0, 4, v225
	v_lshl_add_u64 v[4:5], v[4:5], 0, s[34:35]
	v_and_b32_e32 v0, 0xf0, v0
	v_lshl_add_u64 v[4:5], v[4:5], 0, v[0:1]
	global_load_dwordx4 v[132:135], v[4:5], off offset:1024
	global_load_dwordx4 v[136:139], v[4:5], off offset:2048
	v_add_u32_e32 v4, 0x200, v225
	v_ashrrev_i32_e32 v10, 4, v4
	v_ashrrev_i32_e32 v11, 31, v10
	v_lshlrev_b64 v[4:5], 13, v[10:11]
	v_lshl_add_u64 v[12:13], s[44:45], 0, v[4:5]
	v_lshl_add_u64 v[12:13], v[12:13], 0, s[34:35]
	v_lshl_add_u64 v[12:13], v[12:13], 0, v[0:1]
	global_load_dwordx4 v[140:143], v[12:13], off offset:1024
	global_load_dwordx4 v[144:147], v[12:13], off offset:2048
	s_movk_i32 s23, 0x110
	v_add_u32_e32 v195, 0, v0
	v_mul_lo_u32 v226, v8, s23
	s_movk_i32 s44, 0x140
	v_add_u32_e32 v0, v195, v226
	v_mul_lo_u32 v227, v8, s44
	v_mul_lo_u32 v228, v10, s23
	v_mul_lo_u32 v229, v10, s44
	v_lshlrev_b32_e32 v115, 2, v7
	s_cmp_lt_i32 s0, 0
	s_waitcnt vmcnt(3)
	ds_write_b128 v0, v[132:135]
	v_add_u32_e32 v0, v195, v227
	s_waitcnt vmcnt(2)
	ds_write_b128 v0, v[136:139] offset:17408
	v_add_u32_e32 v0, v195, v228
	s_waitcnt vmcnt(1)
	ds_write_b128 v0, v[140:143]
	v_add_u32_e32 v0, v195, v229
	s_waitcnt vmcnt(0)
	ds_write_b128 v0, v[144:147] offset:17408
	s_waitcnt lgkmcnt(0)
	s_barrier
	s_cbranch_scc1 .LBB0_514
	s_lshl_b32 s23, s0, 1
	s_or_b32 s71, s1, 31
	s_lshl_b32 s0, s31, 1
	s_mul_i32 s1, s51, 0x82
	s_sub_i32 s0, s0, s1
	s_or_b32 s31, s0, 1
	s_and_b32 s0, s51, 3
	s_add_i32 s72, s23, -1
	s_lshl_b32 s73, s70, 7
	s_lshl_b32 s0, s0, 8
	s_add_u32 s0, s36, s0
	v_lshrrev_b32_e32 v7, 2, v225
	s_addc_u32 s1, s37, 0
	v_and_or_b32 v7, v7, 3, v115
	s_add_u32 s0, s0, s41
	v_lshlrev_b32_e32 v0, 3, v225
	v_mul_u32_u24_e32 v231, 0x140, v7
	v_lshlrev_b32_e32 v7, 1, v225
	s_addc_u32 s1, s1, s40
	v_mov_b32_e32 v16, v1
	v_mov_b32_e32 v17, v1
	v_and_b32_e32 v232, 32, v7
	v_and_b32_e32 v233, 24, v0
	v_mul_u32_u24_e32 v234, 0x110, v6
	v_and_b32_e32 v0, 15, v225
	v_lshl_add_u64 v[196:197], s[0:1], 0, v[2:3]
	v_lshl_add_u64 v[198:199], s[0:1], 0, v[4:5]
	v_mov_b32_e32 v2, v1
	v_mov_b32_e32 v3, v1
	v_mov_b32_e32 v4, v1
	v_mov_b32_e32 v5, v1
	v_mov_b32_e32 v6, v1
	v_mov_b32_e32 v7, v1
	v_mov_b32_e32 v8, v1
	v_mov_b32_e32 v9, v1
	v_mov_b32_e32 v10, v1
	v_mov_b32_e32 v11, v1
	v_mov_b32_e32 v12, v1
	v_mov_b32_e32 v13, v1
	v_mov_b32_e32 v14, v1
	v_mov_b32_e32 v15, v1
	v_mov_b32_e32 v235, 0
	v_mov_b64_e32 v[32:33], v[16:17]
	v_mov_b64_e32 v[48:49], v[16:17]
	v_mov_b64_e32 v[64:65], v[16:17]
	v_lshlrev_b32_e32 v0, 4, v0
	s_mov_b32 s74, 0
	v_mov_b64_e32 v[30:31], v[14:15]
	v_mov_b64_e32 v[28:29], v[12:13]
	v_mov_b64_e32 v[26:27], v[10:11]
	v_mov_b64_e32 v[24:25], v[8:9]
	v_mov_b64_e32 v[22:23], v[6:7]
	v_mov_b64_e32 v[20:21], v[4:5]
	v_mov_b64_e32 v[18:19], v[2:3]
	v_mov_b64_e32 v[46:47], v[14:15]
	v_mov_b64_e32 v[44:45], v[12:13]
	v_mov_b64_e32 v[42:43], v[10:11]
	v_mov_b64_e32 v[40:41], v[8:9]
	v_mov_b64_e32 v[38:39], v[6:7]
	v_mov_b64_e32 v[36:37], v[4:5]
	v_mov_b64_e32 v[34:35], v[2:3]
	v_mov_b64_e32 v[62:63], v[14:15]
	v_mov_b64_e32 v[60:61], v[12:13]
	v_mov_b64_e32 v[58:59], v[10:11]
	v_mov_b64_e32 v[56:57], v[8:9]
	v_mov_b64_e32 v[54:55], v[6:7]
	v_mov_b64_e32 v[52:53], v[4:5]
	v_mov_b64_e32 v[50:51], v[2:3]
	v_mov_b32_e32 v230, 0
	s_mov_b32 s75, 0
	v_mov_b32_e32 v66, 0
	v_mov_b32_e32 v67, v235
	v_mov_b32_e32 v68, v235
	v_mov_b32_e32 v69, v235
	v_mov_b32_e32 v70, v235
	v_mov_b32_e32 v71, v235
	v_mov_b32_e32 v72, v235
	v_mov_b32_e32 v73, v235
	v_mov_b32_e32 v74, v235
	v_mov_b32_e32 v75, v235
	v_mov_b32_e32 v76, v235
	v_mov_b32_e32 v77, v235
	v_mov_b32_e32 v78, v235
	v_mov_b32_e32 v79, v235
	v_mov_b32_e32 v80, v235
	v_mov_b32_e32 v81, v235
	s_lshr_b32 s44, s71, 6
	s_add_i32 s44, s44, 1
	s_min_i32 s44, s44, s31
	v_add_u32_e32 v226, v195, v226
	v_add_u32_e32 v227, v195, v227
	v_add_u32_e32 v228, v195, v228
	v_add_u32_e32 v229, v195, v229
	v_add3_u32 v231, v231, v232, v233
	v_add_u32_e32 v252, 0x9500, v231
	v_add3_u32 v234, v234, v194, s73
	v_lshl_add_u64 v[196:197], v[196:197], 0, v[0:1]
	v_lshl_add_u64 v[198:199], v[198:199], 0, v[0:1]
	v_add_co_u32_e32 v196, vcc, 0x5c00000, v196
	s_nop 1
	v_addc_co_u32_e32 v197, vcc, 0, v197, vcc
	v_add_co_u32_e32 v198, vcc, 0x5c00000, v198
	s_nop 1
	v_addc_co_u32_e32 v199, vcc, 0, v199, vcc
	v_lshl_add_u64 v[196:197], v[196:197], 0, s[26:27]
	v_lshl_add_u64 v[198:199], v[198:199], 0, s[26:27]
	global_load_dwordx4 v[132:135], v[196:197], off offset:1024
	global_load_dwordx4 v[140:143], v[198:199], off offset:1024
	s_cmp_lg_u32 s70, 0
	s_cbranch_scc1 .Ldb_top
; __device__ __forceinline__ s16x4 vtr(ldsp p) { return __builtin_bit_cast(s16x4, __builtin_amdgcn_ds_read_tr16_b64_v4i16((LAS v4i16_t*)p)); }
; template <bool DIFF>
; __device__ __forceinline__ void attn_unit(const AttnP& A, int b, int h, int qi, ldsp lds) {
;     ...
;     for (int kt = kt0; kt < nt; ++kt) {
;         if (kt + 1 < nt) LOAD_TILE(kt + 1);
;         if (64 * kt <= qmax_w) {
;             ldsp Kb = lds + (kt & 1) * STAGE; ldsp Vb = Kb + 64 * KP;
;             bf16x8 kf[8]; bf16x8 ka0, ka1, qa; f32x16 s0, s1;
;     ...
;             QK_BLOCK();
;             s16x4 vlo[8], vhi[8];
; #pragma unroll
;             for (int t = 0; t < 2; ++t)
; #pragma unroll
;                 for (int j = 0; j < 4; ++j) { vlo[t * 4 + j] = vtr(Vb + trb + (16 * j) * VP + t * 64); vhi[t * 4 + j] = vtr(Vb + trb + (16 * j + 8) * VP + t * 64); }
;             __builtin_amdgcn_sched_barrier(0);
;             MASK_BLOCK();
;             bool full = (kt == kt0);
;             float psa, psb;
;             if (!full) {
;                 EXPSUM_BLOCK();
;     ...
;             for (int t = 0; t < 2; ++t)
; #pragma unroll
;                 for (int j = 0; j < 4; ++j) {
;                     const bf16x8 vf = (bf16x8){vlo[t * 4 + j][0], vlo[t * 4 + j][1], vlo[t * 4 + j][2], vlo[t * 4 + j][3], vhi[t * 4 + j][0], vhi[t * 4 + j][1], vhi[t * 4 + j][2], vhi[t * 4 + j][3]};
;                     o[t] = __builtin_amdgcn_mfma_f32_32x32x16_bf16(vf, pw[j], o[t], 0, 0, 0);
;                 }
;             if (DIFF) {
; #pragma unroll
;                 for (int t = 2; t < NTD; ++t)
; #pragma unroll
;                     for (int j = 0; j < 4; ++j) { vlo[(t - 2) * 4 + j] = vtr(Vb + trb + (16 * j) * VP + t * 64); vhi[(t - 2) * 4 + j] = vtr(Vb + trb + (16 * j + 8) * VP + t * 64); }
;                 __builtin_amdgcn_sched_barrier(0);
; #pragma unroll
;                 for (int t = 2; t < NTD; ++t)
; #pragma unroll
;                     for (int j = 0; j < 4; ++j) {
;                         const int i = (t - 2) * 4 + j;
;                         const bf16x8 vf = (bf16x8){vlo[i][0], vlo[i][1], vlo[i][2], vlo[i][3], vhi[i][0], vhi[i][1], vhi[i][2], vhi[i][3]};
;                         o[t] = __builtin_amdgcn_mfma_f32_32x32x16_bf16(vf, pw[j], o[t], 0, 0, 0);
;                     }
.Lda_top:
	s_and_b64 vcc, exec, s[16:17]
	s_cbranch_vccz .Lda_gen
	s_cmp_lt_i32 s75, 1
	s_cbranch_scc1 .Lda_gen
	s_add_i32 s0, s31, -3
	s_cmp_gt_i32 s75, s0
	s_cbranch_scc1 .Lda_gen
	s_add_i32 s23, s31, -3
	s_bitcmp1_b32 s75, 0
	s_cbranch_scc1 .Lda_s_odd
.Lda_s_even:
	ds_read_b64_tr_b16 v[148:149], v252 offset:17472
	ds_read_b64_tr_b16 v[150:151], v252 offset:20032
	ds_read_b64_tr_b16 v[152:153], v252 offset:17408
	ds_read_b64_tr_b16 v[154:155], v252 offset:19968
	ds_read_b64_tr_b16 v[156:157], v252 offset:22592
	ds_read_b64_tr_b16 v[158:159], v252 offset:25152
	ds_read_b64_tr_b16 v[160:161], v252 offset:22528
	ds_read_b64_tr_b16 v[162:163], v252 offset:25088
	ds_read_b64_tr_b16 v[164:165], v252 offset:27712
	ds_read_b64_tr_b16 v[166:167], v252 offset:30272
	ds_read_b64_tr_b16 v[168:169], v252 offset:27648
	ds_read_b64_tr_b16 v[170:171], v252 offset:30208
	ds_read_b64_tr_b16 v[172:173], v252 offset:32768
	ds_read_b64_tr_b16 v[174:175], v252 offset:35328
	ds_read_b64_tr_b16 v[176:177], v252 offset:32832
	ds_read_b64_tr_b16 v[178:179], v252 offset:35392
	s_waitcnt lgkmcnt(14)
	v_mfma_f32_32x32x16_bf16 v[34:49], v[148:151], v[98:101], v[34:49]
	ds_read_b64_tr_b16 v[90:91], v252 offset:17536
	ds_read_b64_tr_b16 v[92:93], v252 offset:20096
	s_waitcnt lgkmcnt(14)
	v_mfma_f32_32x32x16_bf16 v[50:65], v[152:155], v[98:101], v[50:65]
	ds_read_b64_tr_b16 v[94:95], v252 offset:17600
	ds_read_b64_tr_b16 v[96:97], v252 offset:20160
	s_waitcnt lgkmcnt(14)
	v_mfma_f32_32x32x16_bf16 v[34:49], v[156:159], v[102:105], v[34:49]
	ds_read_b64_tr_b16 v[106:107], v252 offset:22656
	ds_read_b64_tr_b16 v[108:109], v252 offset:25216
	s_waitcnt lgkmcnt(14)
	v_mfma_f32_32x32x16_bf16 v[50:65], v[160:163], v[102:105], v[50:65]
	ds_read_b64_tr_b16 v[110:111], v252 offset:22720
	ds_read_b64_tr_b16 v[112:113], v252 offset:25280
	s_waitcnt lgkmcnt(14)
	v_mfma_f32_32x32x16_bf16 v[34:49], v[164:167], v[82:85], v[34:49]
	ds_read_b64_tr_b16 v[240:241], v252 offset:27776
	ds_read_b64_tr_b16 v[242:243], v252 offset:30336
	s_waitcnt lgkmcnt(14)
	v_mfma_f32_32x32x16_bf16 v[50:65], v[168:171], v[82:85], v[50:65]
	ds_read_b64_tr_b16 v[148:149], v252 offset:27840
	ds_read_b64_tr_b16 v[150:151], v252 offset:30400
	s_waitcnt lgkmcnt(14)
	v_mfma_f32_32x32x16_bf16 v[50:65], v[172:175], v[86:89], v[50:65]
	ds_read_b64_tr_b16 v[152:153], v252 offset:32896
	ds_read_b64_tr_b16 v[154:155], v252 offset:35456
	s_waitcnt lgkmcnt(14)
	v_mfma_f32_32x32x16_bf16 v[34:49], v[176:179], v[86:89], v[34:49]
	ds_read_b64_tr_b16 v[156:157], v252 offset:32960
	ds_read_b64_tr_b16 v[158:159], v252 offset:35520
	s_waitcnt lgkmcnt(14)
	v_mfma_f32_32x32x16_bf16 v[18:33], v[90:93], v[98:101], v[18:33]
	ds_read_b128 v[160:163], v234
	s_waitcnt lgkmcnt(13)
	v_mfma_f32_32x32x16_bf16 v[2:17], v[94:97], v[98:101], v[2:17]
	ds_read_b128 v[164:167], v234 offset:8704
	s_waitcnt lgkmcnt(12)
	v_mfma_f32_32x32x16_bf16 v[18:33], v[106:109], v[102:105], v[18:33]
	ds_read_b128 v[168:171], v234 offset:32
	s_waitcnt lgkmcnt(11)
	v_mfma_f32_32x32x16_bf16 v[2:17], v[110:113], v[102:105], v[2:17]
	ds_read_b128 v[172:175], v234 offset:8736
	s_waitcnt lgkmcnt(10)
	v_mfma_f32_32x32x16_bf16 v[18:33], v[240:243], v[82:85], v[18:33]
	ds_read_b128 v[176:179], v234 offset:64
	s_waitcnt lgkmcnt(9)
	v_mfma_f32_32x32x16_bf16 v[2:17], v[148:151], v[82:85], v[2:17]
	ds_read_b128 v[240:243], v234 offset:8768
	s_waitcnt lgkmcnt(8)
	v_mfma_f32_32x32x16_bf16 v[18:33], v[152:155], v[86:89], v[18:33]
	ds_read_b128 v[148:151], v234 offset:96
	s_waitcnt lgkmcnt(7)
	v_mfma_f32_32x32x16_bf16 v[2:17], v[156:159], v[86:89], v[2:17]
	ds_read_b128 v[152:155], v234 offset:8800
	s_waitcnt lgkmcnt(7)
	v_mfma_f32_32x32x16_bf16 v[98:113], v[160:163], v[116:119], v[66:81]
	s_waitcnt lgkmcnt(6)
	v_mfma_f32_32x32x16_bf16 v[82:97], v[164:167], v[116:119], v[66:81]
	s_waitcnt lgkmcnt(5)
	v_mfma_f32_32x32x16_bf16 v[98:113], v[168:171], v[120:123], v[98:113]
	s_waitcnt lgkmcnt(4)
	v_mfma_f32_32x32x16_bf16 v[82:97], v[172:175], v[120:123], v[82:97]
	s_waitcnt lgkmcnt(3)
	v_mfma_f32_32x32x16_bf16 v[98:113], v[176:179], v[124:127], v[98:113]
	s_waitcnt lgkmcnt(2)
	v_mfma_f32_32x32x16_bf16 v[82:97], v[240:243], v[124:127], v[82:97]
	s_waitcnt lgkmcnt(1)
	v_mfma_f32_32x32x16_bf16 v[98:113], v[148:151], v[128:131], v[98:113]
	s_waitcnt lgkmcnt(0)
	v_mfma_f32_32x32x16_bf16 v[82:97], v[152:155], v[128:131], v[82:97]
	s_waitcnt vmcnt(0)
	ds_write_b128 v226, v[132:135] offset:38144
	ds_write_b128 v228, v[140:143] offset:38144
	ds_write_b128 v227, v[136:139] offset:17408
	ds_write_b128 v229, v[144:147] offset:17408
	global_load_dwordx4 v[136:139], v[196:197], off offset:2048
	global_load_dwordx4 v[144:147], v[198:199], off offset:2048
	v_lshl_add_u64 v[196:197], v[196:197], 0, s[26:27]
	v_lshl_add_u64 v[198:199], v[198:199], 0, s[26:27]
	global_load_dwordx4 v[132:135], v[196:197], off offset:1024
	global_load_dwordx4 v[140:143], v[198:199], off offset:1024
	v_exp_f32_e32 v148, v98
	v_exp_f32_e32 v164, v82
	v_exp_f32_e32 v149, v99
	v_exp_f32_e32 v165, v83
	v_add_f32_e32 v237, 0, v148
	v_add_f32_e32 v238, 0, v164
	v_exp_f32_e32 v150, v100
	v_exp_f32_e32 v166, v84
	v_add_f32_e32 v237, v149, v237
	v_add_f32_e32 v238, v165, v238
	v_exp_f32_e32 v151, v101
	v_exp_f32_e32 v167, v85
	v_add_f32_e32 v237, v150, v237
	v_add_f32_e32 v238, v166, v238
	v_exp_f32_e32 v152, v102
	v_exp_f32_e32 v168, v86
	v_add_f32_e32 v237, v151, v237
	v_add_f32_e32 v238, v167, v238
	v_exp_f32_e32 v153, v103
	v_exp_f32_e32 v169, v87
	v_add_f32_e32 v237, v152, v237
	v_add_f32_e32 v238, v168, v238
	v_exp_f32_e32 v154, v104
	v_exp_f32_e32 v170, v88
	v_add_f32_e32 v237, v153, v237
	v_add_f32_e32 v238, v169, v238
	v_exp_f32_e32 v155, v105
	v_exp_f32_e32 v171, v89
	v_add_f32_e32 v237, v154, v237
	v_add_f32_e32 v238, v170, v238
	v_exp_f32_e32 v156, v106
	v_exp_f32_e32 v172, v90
	v_add_f32_e32 v237, v155, v237
	v_add_f32_e32 v238, v171, v238
	v_exp_f32_e32 v157, v107
	v_exp_f32_e32 v173, v91
	v_add_f32_e32 v237, v156, v237
	v_add_f32_e32 v238, v172, v238
	v_exp_f32_e32 v158, v108
	v_exp_f32_e32 v174, v92
	v_add_f32_e32 v237, v157, v237
	v_add_f32_e32 v238, v173, v238
	v_exp_f32_e32 v159, v109
	v_exp_f32_e32 v175, v93
	v_add_f32_e32 v237, v158, v237
	v_add_f32_e32 v238, v174, v238
	v_exp_f32_e32 v160, v110
	v_exp_f32_e32 v176, v94
	v_add_f32_e32 v237, v159, v237
	v_add_f32_e32 v238, v175, v238
	v_exp_f32_e32 v161, v111
	v_exp_f32_e32 v177, v95
	v_add_f32_e32 v237, v160, v237
	v_add_f32_e32 v238, v176, v238
	v_exp_f32_e32 v162, v112
	v_exp_f32_e32 v178, v96
	v_add_f32_e32 v237, v161, v237
	v_add_f32_e32 v238, v177, v238
	v_exp_f32_e32 v163, v113
	v_exp_f32_e32 v179, v97
	v_add_f32_e32 v237, v162, v237
	v_add_f32_e32 v238, v178, v238
	s_nop 0
	v_add_f32_e32 v237, v163, v237
	v_add_f32_e32 v238, v179, v238
	v_add_f32_e32 v204, v237, v238
	v_cmp_lt_f32_e32 vcc, s85, v204
	s_cbranch_vccnz .Lda_s_slow
; __device__ __forceinline__ unsigned cvtpk(float lo, float hi) { f32x2 v = {lo, hi}; bf16x2_t b = __builtin_convertvector(v, bf16x2_t); return __builtin_bit_cast(unsigned, b); }
; template <bool DIFF>
; __device__ __forceinline__ void attn_unit(const AttnP& A, int b, int h, int qi, ldsp lds) {
;     ...
;     for (int kt = kt0; kt < nt; ++kt) {
;         if (kt + 1 < nt) LOAD_TILE(kt + 1);
;         if (64 * kt <= qmax_w) {
;             ldsp Kb = lds + (kt & 1) * STAGE; ldsp Vb = Kb + 64 * KP;
;             bf16x8 kf[8]; bf16x8 ka0, ka1, qa; f32x16 s0, s1;
;     ...
;             bf16x8 pw[4];
; #pragma unroll
;             for (int j = 0; j < 4; ++j) {
;                 u32x4 pk;
;                 if (j < 2) { const int rb = 8 * (j & 1); pk.x = cvtpk(s0[rb], s0[rb + 1]); pk.y = cvtpk(s0[rb + 2], s0[rb + 3]); pk.z = cvtpk(s0[rb + 4], s0[rb + 5]); pk.w = cvtpk(s0[rb + 6], s0[rb + 7]); }
;                 else { const int rb = 8 * (j & 1); pk.x = cvtpk(s1[rb], s1[rb + 1]); pk.y = cvtpk(s1[rb + 2], s1[rb + 3]); pk.z = cvtpk(s1[rb + 4], s1[rb + 5]); pk.w = cvtpk(s1[rb + 6], s1[rb + 7]); }
;                 pw[j] = __builtin_bit_cast(bf16x8, pk);
;             }
	v_cvt_pk_bf16_f32 v98, v148, v149
	v_cvt_pk_bf16_f32 v99, v150, v151
	v_cvt_pk_bf16_f32 v100, v152, v153
	v_cvt_pk_bf16_f32 v101, v154, v155
	v_cvt_pk_bf16_f32 v102, v156, v157
	v_cvt_pk_bf16_f32 v103, v158, v159
	v_cvt_pk_bf16_f32 v104, v160, v161
	v_cvt_pk_bf16_f32 v105, v162, v163
	v_cvt_pk_bf16_f32 v82, v164, v165
	v_cvt_pk_bf16_f32 v83, v166, v167
	v_cvt_pk_bf16_f32 v84, v168, v169
	v_cvt_pk_bf16_f32 v85, v170, v171
	v_cvt_pk_bf16_f32 v86, v172, v173
	v_cvt_pk_bf16_f32 v87, v174, v175
	v_cvt_pk_bf16_f32 v88, v176, v177
	v_cvt_pk_bf16_f32 v89, v178, v179
	v_add_f32_e32 v230, v204, v230
	s_waitcnt lgkmcnt(0)
	s_barrier
	s_add_i32 s75, s75, 1
	s_add_i32 s74, s74, 64
	s_cmp_gt_i32 s75, s23
	s_cbranch_scc1 .Lda_gen
.Lda_s_odd:
	ds_read_b64_tr_b16 v[148:149], v231 offset:17472
	ds_read_b64_tr_b16 v[150:151], v231 offset:20032
	ds_read_b64_tr_b16 v[152:153], v231 offset:17408
	ds_read_b64_tr_b16 v[154:155], v231 offset:19968
	ds_read_b64_tr_b16 v[156:157], v231 offset:22592
	ds_read_b64_tr_b16 v[158:159], v231 offset:25152
	ds_read_b64_tr_b16 v[160:161], v231 offset:22528
	ds_read_b64_tr_b16 v[162:163], v231 offset:25088
	ds_read_b64_tr_b16 v[164:165], v231 offset:27712
	ds_read_b64_tr_b16 v[166:167], v231 offset:30272
	ds_read_b64_tr_b16 v[168:169], v231 offset:27648
	ds_read_b64_tr_b16 v[170:171], v231 offset:30208
	ds_read_b64_tr_b16 v[172:173], v231 offset:32768
	ds_read_b64_tr_b16 v[174:175], v231 offset:35328
	ds_read_b64_tr_b16 v[176:177], v231 offset:32832
	ds_read_b64_tr_b16 v[178:179], v231 offset:35392
	s_waitcnt lgkmcnt(14)
	v_mfma_f32_32x32x16_bf16 v[34:49], v[148:151], v[98:101], v[34:49]
	ds_read_b64_tr_b16 v[90:91], v231 offset:17536
	ds_read_b64_tr_b16 v[92:93], v231 offset:20096
	s_waitcnt lgkmcnt(14)
	v_mfma_f32_32x32x16_bf16 v[50:65], v[152:155], v[98:101], v[50:65]
	ds_read_b64_tr_b16 v[94:95], v231 offset:17600
	ds_read_b64_tr_b16 v[96:97], v231 offset:20160
	s_waitcnt lgkmcnt(14)
	v_mfma_f32_32x32x16_bf16 v[34:49], v[156:159], v[102:105], v[34:49]
	ds_read_b64_tr_b16 v[106:107], v231 offset:22656
	ds_read_b64_tr_b16 v[108:109], v231 offset:25216
	s_waitcnt lgkmcnt(14)
	v_mfma_f32_32x32x16_bf16 v[50:65], v[160:163], v[102:105], v[50:65]
	ds_read_b64_tr_b16 v[110:111], v231 offset:22720
	ds_read_b64_tr_b16 v[112:113], v231 offset:25280
	s_waitcnt lgkmcnt(14)
	v_mfma_f32_32x32x16_bf16 v[34:49], v[164:167], v[82:85], v[34:49]
	ds_read_b64_tr_b16 v[240:241], v231 offset:27776
	ds_read_b64_tr_b16 v[242:243], v231 offset:30336
	s_waitcnt lgkmcnt(14)
	v_mfma_f32_32x32x16_bf16 v[50:65], v[168:171], v[82:85], v[50:65]
	ds_read_b64_tr_b16 v[148:149], v231 offset:27840
	ds_read_b64_tr_b16 v[150:151], v231 offset:30400
	s_waitcnt lgkmcnt(14)
	v_mfma_f32_32x32x16_bf16 v[50:65], v[172:175], v[86:89], v[50:65]
	ds_read_b64_tr_b16 v[152:153], v231 offset:32896
	ds_read_b64_tr_b16 v[154:155], v231 offset:35456
	s_waitcnt lgkmcnt(14)
	v_mfma_f32_32x32x16_bf16 v[34:49], v[176:179], v[86:89], v[34:49]
	ds_read_b64_tr_b16 v[156:157], v231 offset:32960
	ds_read_b64_tr_b16 v[158:159], v231 offset:35520
	s_waitcnt lgkmcnt(14)
	v_mfma_f32_32x32x16_bf16 v[18:33], v[90:93], v[98:101], v[18:33]
	ds_read_b128 v[160:163], v234 offset:38144
	s_waitcnt lgkmcnt(13)
	v_mfma_f32_32x32x16_bf16 v[2:17], v[94:97], v[98:101], v[2:17]
	ds_read_b128 v[164:167], v234 offset:46848
	s_waitcnt lgkmcnt(12)
	v_mfma_f32_32x32x16_bf16 v[18:33], v[106:109], v[102:105], v[18:33]
	ds_read_b128 v[168:171], v234 offset:38176
	s_waitcnt lgkmcnt(11)
	v_mfma_f32_32x32x16_bf16 v[2:17], v[110:113], v[102:105], v[2:17]
	ds_read_b128 v[172:175], v234 offset:46880
	s_waitcnt lgkmcnt(10)
	v_mfma_f32_32x32x16_bf16 v[18:33], v[240:243], v[82:85], v[18:33]
	ds_read_b128 v[176:179], v234 offset:38208
	s_waitcnt lgkmcnt(9)
	v_mfma_f32_32x32x16_bf16 v[2:17], v[148:151], v[82:85], v[2:17]
	ds_read_b128 v[240:243], v234 offset:46912
	s_waitcnt lgkmcnt(8)
	v_mfma_f32_32x32x16_bf16 v[18:33], v[152:155], v[86:89], v[18:33]
	ds_read_b128 v[148:151], v234 offset:38240
	s_waitcnt lgkmcnt(7)
; __device__ __forceinline__ s16x4 vtr(ldsp p) { return __builtin_bit_cast(s16x4, __builtin_amdgcn_ds_read_tr16_b64_v4i16((LAS v4i16_t*)p)); }
; template <bool DIFF>
; __device__ __forceinline__ void attn_unit(const AttnP& A, int b, int h, int qi, ldsp lds) {
;     ...
;             QK_BLOCK();
;             s16x4 vlo[8], vhi[8];
; #pragma unroll
;             for (int t = 0; t < 2; ++t)
; #pragma unroll
;                 for (int j = 0; j < 4; ++j) { vlo[t * 4 + j] = vtr(Vb + trb + (16 * j) * VP + t * 64); vhi[t * 4 + j] = vtr(Vb + trb + (16 * j + 8) * VP + t * 64); }
;             __builtin_amdgcn_sched_barrier(0);
;             MASK_BLOCK();
;             bool full = (kt == kt0);
;             float psa, psb;
;             if (!full) {
;                 EXPSUM_BLOCK();
;                 if (__any(psa + psb > 1.0e18f)) { full = true; QK_BLOCK();
; #pragma unroll
;                     for (int t = 0; t < 2; ++t)
; #pragma unroll
;                         for (int j = 0; j < 4; ++j) { vlo[t * 4 + j] = vtr(Vb + trb + (16 * j) * VP + t * 64); vhi[t * 4 + j] = vtr(Vb + trb + (16 * j + 8) * VP + t * 64); }
;                     MASK_BLOCK(); }
;             }
;             if (full) {
;                 float ma = fmaxf(fmaxf(s0[0], s0[1]), s1[0]), mb = fmaxf(fmaxf(s0[2], s0[3]), s1[1]);
;                 ma = fmaxf(fmaxf(ma, s1[2]), s1[3]);
; #pragma unroll
;                 for (int r = 4; r < 16; r += 4) { ma = fmaxf(fmaxf(ma, s0[r]), s0[r + 1]); mb = fmaxf(fmaxf(mb, s0[r + 2]), s0[r + 3]); ma = fmaxf(fmaxf(ma, s1[r]), s1[r + 1]); mb = fmaxf(fmaxf(mb, s1[r + 2]), s1[r + 3]); }
;                 const float rm = swap32_max(fmaxf(ma, mb));
;                 const float dl = (kt == kt0) ? ((rm == -INFINITY) ? 0.f : rm) : fmaxf(rm, 0.f);
;                 mhat += dl;
; #pragma unroll
;                 for (int r = 0; r < 16; ++r) { s0[r] -= dl; s1[r] -= dl; negm[r] = -mhat; }
;                 const float f = (kt == kt0) ? 1.0f : __builtin_amdgcn_exp2f(-dl);
;                 l_run *= f;
; #pragma unroll
;                 for (int t = 0; t < NTD; ++t)
; #pragma unroll
;                     for (int r = 0; r < 16; ++r) o[t][r] *= f;
;                 EXPSUM_BLOCK();
;             }
;             l_run += psa + psb;
;     ...
;             bf16x8 pw[4];
; #pragma unroll
;             for (int j = 0; j < 4; ++j) {
;                 u32x4 pk;
	v_mfma_f32_32x32x16_bf16 v[2:17], v[156:159], v[86:89], v[2:17]
	ds_read_b128 v[152:155], v234 offset:46944
	s_waitcnt lgkmcnt(7)
	v_mfma_f32_32x32x16_bf16 v[98:113], v[160:163], v[116:119], v[66:81]
	s_waitcnt lgkmcnt(6)
	v_mfma_f32_32x32x16_bf16 v[82:97], v[164:167], v[116:119], v[66:81]
	s_waitcnt lgkmcnt(5)
	v_mfma_f32_32x32x16_bf16 v[98:113], v[168:171], v[120:123], v[98:113]
	s_waitcnt lgkmcnt(4)
	v_mfma_f32_32x32x16_bf16 v[82:97], v[172:175], v[120:123], v[82:97]
	s_waitcnt lgkmcnt(3)
	v_mfma_f32_32x32x16_bf16 v[98:113], v[176:179], v[124:127], v[98:113]
	s_waitcnt lgkmcnt(2)
	v_mfma_f32_32x32x16_bf16 v[82:97], v[240:243], v[124:127], v[82:97]
	s_waitcnt lgkmcnt(1)
	v_mfma_f32_32x32x16_bf16 v[98:113], v[148:151], v[128:131], v[98:113]
	s_waitcnt lgkmcnt(0)
	v_mfma_f32_32x32x16_bf16 v[82:97], v[152:155], v[128:131], v[82:97]
	s_waitcnt vmcnt(0)
	ds_write_b128 v226, v[132:135]
	ds_write_b128 v228, v[140:143]
	ds_write_b128 v227, v[136:139] offset:55552
	ds_write_b128 v229, v[144:147] offset:55552
	global_load_dwordx4 v[136:139], v[196:197], off offset:2048
	global_load_dwordx4 v[144:147], v[198:199], off offset:2048
	v_lshl_add_u64 v[196:197], v[196:197], 0, s[26:27]
	v_lshl_add_u64 v[198:199], v[198:199], 0, s[26:27]
	global_load_dwordx4 v[132:135], v[196:197], off offset:1024
	global_load_dwordx4 v[140:143], v[198:199], off offset:1024
	v_exp_f32_e32 v148, v98
	v_exp_f32_e32 v164, v82
	v_exp_f32_e32 v149, v99
	v_exp_f32_e32 v165, v83
	v_add_f32_e32 v237, 0, v148
	v_add_f32_e32 v238, 0, v164
	v_exp_f32_e32 v150, v100
	v_exp_f32_e32 v166, v84
	v_add_f32_e32 v237, v149, v237
	v_add_f32_e32 v238, v165, v238
	v_exp_f32_e32 v151, v101
	v_exp_f32_e32 v167, v85
	v_add_f32_e32 v237, v150, v237
	v_add_f32_e32 v238, v166, v238
	v_exp_f32_e32 v152, v102
	v_exp_f32_e32 v168, v86
	v_add_f32_e32 v237, v151, v237
	v_add_f32_e32 v238, v167, v238
	v_exp_f32_e32 v153, v103
	v_exp_f32_e32 v169, v87
	v_add_f32_e32 v237, v152, v237
	v_add_f32_e32 v238, v168, v238
	v_exp_f32_e32 v154, v104
	v_exp_f32_e32 v170, v88
	v_add_f32_e32 v237, v153, v237
	v_add_f32_e32 v238, v169, v238
	v_exp_f32_e32 v155, v105
	v_exp_f32_e32 v171, v89
	v_add_f32_e32 v237, v154, v237
	v_add_f32_e32 v238, v170, v238
	v_exp_f32_e32 v156, v106
	v_exp_f32_e32 v172, v90
	v_add_f32_e32 v237, v155, v237
	v_add_f32_e32 v238, v171, v238
	v_exp_f32_e32 v157, v107
	v_exp_f32_e32 v173, v91
	v_add_f32_e32 v237, v156, v237
	v_add_f32_e32 v238, v172, v238
	v_exp_f32_e32 v158, v108
	v_exp_f32_e32 v174, v92
	v_add_f32_e32 v237, v157, v237
	v_add_f32_e32 v238, v173, v238
	v_exp_f32_e32 v159, v109
	v_exp_f32_e32 v175, v93
	v_add_f32_e32 v237, v158, v237
	v_add_f32_e32 v238, v174, v238
	v_exp_f32_e32 v160, v110
	v_exp_f32_e32 v176, v94
	v_add_f32_e32 v237, v159, v237
	v_add_f32_e32 v238, v175, v238
	v_exp_f32_e32 v161, v111
	v_exp_f32_e32 v177, v95
	v_add_f32_e32 v237, v160, v237
	v_add_f32_e32 v238, v176, v238
	v_exp_f32_e32 v162, v112
	v_exp_f32_e32 v178, v96
	v_add_f32_e32 v237, v161, v237
	v_add_f32_e32 v238, v177, v238
	v_exp_f32_e32 v163, v113
	v_exp_f32_e32 v179, v97
	v_add_f32_e32 v237, v162, v237
	v_add_f32_e32 v238, v178, v238
	s_nop 0
	v_add_f32_e32 v237, v163, v237
	v_add_f32_e32 v238, v179, v238
	v_add_f32_e32 v204, v237, v238
	v_cmp_lt_f32_e32 vcc, s85, v204
	s_cbranch_vccnz .Lda_s_slow
	v_cvt_pk_bf16_f32 v98, v148, v149
	v_cvt_pk_bf16_f32 v99, v150, v151
	v_cvt_pk_bf16_f32 v100, v152, v153
	v_cvt_pk_bf16_f32 v101, v154, v155
	v_cvt_pk_bf16_f32 v102, v156, v157
	v_cvt_pk_bf16_f32 v103, v158, v159
	v_cvt_pk_bf16_f32 v104, v160, v161
	v_cvt_pk_bf16_f32 v105, v162, v163
	v_cvt_pk_bf16_f32 v82, v164, v165
	v_cvt_pk_bf16_f32 v83, v166, v167
	v_cvt_pk_bf16_f32 v84, v168, v169
	v_cvt_pk_bf16_f32 v85, v170, v171
	v_cvt_pk_bf16_f32 v86, v172, v173
	v_cvt_pk_bf16_f32 v87, v174, v175
	v_cvt_pk_bf16_f32 v88, v176, v177
	v_cvt_pk_bf16_f32 v89, v178, v179
	v_add_f32_e32 v230, v204, v230
	s_waitcnt lgkmcnt(0)
	s_barrier
	s_add_i32 s75, s75, 1
	s_add_i32 s74, s74, 64
	s_cmp_le_i32 s75, s23
	s_cbranch_scc1 .Lda_s_even

; __device__ __forceinline__ s16x4 vtr(ldsp p) { return __builtin_bit_cast(s16x4, __builtin_amdgcn_ds_read_tr16_b64_v4i16((LAS v4i16_t*)p)); }
; template <bool DIFF>
; __device__ __forceinline__ void attn_unit(const AttnP& A, int b, int h, int qi, ldsp lds) {
;     ...
;             QK_BLOCK();
;             s16x4 vlo[8], vhi[8];
; #pragma unroll
;             for (int t = 0; t < 2; ++t)
; #pragma unroll
;                 for (int j = 0; j < 4; ++j) { vlo[t * 4 + j] = vtr(Vb + trb + (16 * j) * VP + t * 64); vhi[t * 4 + j] = vtr(Vb + trb + (16 * j + 8) * VP + t * 64); }
;             __builtin_amdgcn_sched_barrier(0);
;             MASK_BLOCK();
;             bool full = (kt == kt0);
;             float psa, psb;
;             if (!full) {
;                 EXPSUM_BLOCK();
;                 if (__any(psa + psb > 1.0e18f)) { full = true; QK_BLOCK();
; #pragma unroll
;                     for (int t = 0; t < 2; ++t)
; #pragma unroll
;                         for (int j = 0; j < 4; ++j) { vlo[t * 4 + j] = vtr(Vb + trb + (16 * j) * VP + t * 64); vhi[t * 4 + j] = vtr(Vb + trb + (16 * j + 8) * VP + t * 64); }
;                     MASK_BLOCK(); }
;             }
;             if (full) {
;                 float ma = fmaxf(fmaxf(s0[0], s0[1]), s1[0]), mb = fmaxf(fmaxf(s0[2], s0[3]), s1[1]);
;                 ma = fmaxf(fmaxf(ma, s1[2]), s1[3]);
; #pragma unroll
;                 for (int r = 4; r < 16; r += 4) { ma = fmaxf(fmaxf(ma, s0[r]), s0[r + 1]); mb = fmaxf(fmaxf(mb, s0[r + 2]), s0[r + 3]); ma = fmaxf(fmaxf(ma, s1[r]), s1[r + 1]); mb = fmaxf(fmaxf(mb, s1[r + 2]), s1[r + 3]); }
;                 const float rm = swap32_max(fmaxf(ma, mb));
;                 const float dl = (kt == kt0) ? ((rm == -INFINITY) ? 0.f : rm) : fmaxf(rm, 0.f);
;                 mhat += dl;
; #pragma unroll
;                 for (int r = 0; r < 16; ++r) { s0[r] -= dl; s1[r] -= dl; negm[r] = -mhat; }
;                 const float f = (kt == kt0) ? 1.0f : __builtin_amdgcn_exp2f(-dl);
;                 l_run *= f;
; #pragma unroll
;                 for (int t = 0; t < NTD; ++t)
; #pragma unroll
;                     for (int r = 0; r < 16; ++r) o[t][r] *= f;
;                 EXPSUM_BLOCK();
;             }
;             l_run += psa + psb;
;     ...
;             bf16x8 pw[4];
; #pragma unroll
;             for (int j = 0; j < 4; ++j) {
;                 u32x4 pk;
.Ldb_top:
	s_and_b64 vcc, exec, s[16:17]
	s_cbranch_vccz .Ldb_gen
	s_cmp_lt_i32 s75, 2
	s_cbranch_scc1 .Ldb_gen
	s_add_i32 s0, s31, -2
	s_cmp_gt_i32 s75, s0
	s_cbranch_scc1 .Ldb_gen
	s_add_i32 s23, s31, -2
	s_bitcmp1_b32 s75, 0
	s_cbranch_scc1 .Ldb_s_odd
.Ldb_s_even:
	v_exp_f32_e32 v148, v98
	v_exp_f32_e32 v164, v82
	v_exp_f32_e32 v149, v99
	v_exp_f32_e32 v165, v83
	v_add_f32_e32 v237, 0, v148
	v_add_f32_e32 v238, 0, v164
	v_exp_f32_e32 v150, v100
	v_exp_f32_e32 v166, v84
	v_add_f32_e32 v237, v149, v237
	v_add_f32_e32 v238, v165, v238
	v_exp_f32_e32 v151, v101
	v_exp_f32_e32 v167, v85
	v_add_f32_e32 v237, v150, v237
	v_add_f32_e32 v238, v166, v238
	v_exp_f32_e32 v152, v102
	v_exp_f32_e32 v168, v86
	v_add_f32_e32 v237, v151, v237
	v_add_f32_e32 v238, v167, v238
	v_exp_f32_e32 v153, v103
	v_exp_f32_e32 v169, v87
	v_add_f32_e32 v237, v152, v237
	v_add_f32_e32 v238, v168, v238
	v_exp_f32_e32 v154, v104
	v_exp_f32_e32 v170, v88
	v_add_f32_e32 v237, v153, v237
	v_add_f32_e32 v238, v169, v238
	v_exp_f32_e32 v155, v105
	v_exp_f32_e32 v171, v89
	v_add_f32_e32 v237, v154, v237
	v_add_f32_e32 v238, v170, v238
	v_exp_f32_e32 v156, v106
	v_exp_f32_e32 v172, v90
	v_add_f32_e32 v237, v155, v237
	v_add_f32_e32 v238, v171, v238
	v_exp_f32_e32 v157, v107
	v_exp_f32_e32 v173, v91
	v_add_f32_e32 v237, v156, v237
	v_add_f32_e32 v238, v172, v238
	v_exp_f32_e32 v158, v108
	v_exp_f32_e32 v174, v92
	v_add_f32_e32 v237, v157, v237
	v_add_f32_e32 v238, v173, v238
	v_exp_f32_e32 v159, v109
	v_exp_f32_e32 v175, v93
	v_add_f32_e32 v237, v158, v237
	v_add_f32_e32 v238, v174, v238
	v_exp_f32_e32 v160, v110
	v_exp_f32_e32 v176, v94
	v_add_f32_e32 v237, v159, v237
	v_add_f32_e32 v238, v175, v238
	v_exp_f32_e32 v161, v111
	v_exp_f32_e32 v177, v95
	v_add_f32_e32 v237, v160, v237
	v_add_f32_e32 v238, v176, v238
	v_exp_f32_e32 v162, v112
	v_exp_f32_e32 v178, v96
	v_add_f32_e32 v237, v161, v237
	v_add_f32_e32 v238, v177, v238
	v_exp_f32_e32 v163, v113
	v_exp_f32_e32 v179, v97
	v_add_f32_e32 v237, v162, v237
	v_add_f32_e32 v238, v178, v238
	s_nop 0
	v_add_f32_e32 v237, v163, v237
	v_add_f32_e32 v238, v179, v238
	v_add_f32_e32 v204, v237, v238
	v_cmp_lt_f32_e32 vcc, s85, v204
	s_cbranch_vccnz .Ldb_s_slow
	ds_read_b64_tr_b16 v[90:91], v252 offset:17472
	ds_read_b64_tr_b16 v[92:93], v252 offset:20032
	ds_read_b64_tr_b16 v[94:95], v252 offset:17408
	ds_read_b64_tr_b16 v[96:97], v252 offset:19968
	ds_read_b64_tr_b16 v[106:107], v252 offset:22592
	ds_read_b64_tr_b16 v[108:109], v252 offset:25152
	ds_read_b64_tr_b16 v[110:111], v252 offset:22528
	ds_read_b64_tr_b16 v[112:113], v252 offset:25088
	ds_read_b64_tr_b16 v[240:241], v252 offset:27712
	ds_read_b64_tr_b16 v[242:243], v252 offset:30272
	v_cvt_pk_bf16_f32 v98, v148, v149
	v_cvt_pk_bf16_f32 v99, v150, v151
	v_cvt_pk_bf16_f32 v100, v152, v153
	v_cvt_pk_bf16_f32 v101, v154, v155
	v_cvt_pk_bf16_f32 v102, v156, v157
	v_cvt_pk_bf16_f32 v103, v158, v159
	v_cvt_pk_bf16_f32 v104, v160, v161
	v_cvt_pk_bf16_f32 v105, v162, v163
	v_cvt_pk_bf16_f32 v82, v164, v165
	v_cvt_pk_bf16_f32 v83, v166, v167
	v_cvt_pk_bf16_f32 v84, v168, v169
	v_cvt_pk_bf16_f32 v85, v170, v171
	v_cvt_pk_bf16_f32 v86, v172, v173
	v_cvt_pk_bf16_f32 v87, v174, v175
	v_cvt_pk_bf16_f32 v88, v176, v177
	v_cvt_pk_bf16_f32 v89, v178, v179
	v_add_f32_e32 v230, v204, v230
	ds_read_b64_tr_b16 v[148:149], v252 offset:27648
	ds_read_b64_tr_b16 v[150:151], v252 offset:30208
	ds_read_b64_tr_b16 v[152:153], v252 offset:32768
	ds_read_b64_tr_b16 v[154:155], v252 offset:35328
	ds_read_b64_tr_b16 v[156:157], v252 offset:32832
	ds_read_b64_tr_b16 v[158:159], v252 offset:35392
	s_setprio 1
	s_waitcnt lgkmcnt(14)
	v_mfma_f32_32x32x16_bf16 v[34:49], v[90:93], v[98:101], v[34:49]
	ds_read_b64_tr_b16 v[160:161], v252 offset:17536
	ds_read_b64_tr_b16 v[162:163], v252 offset:20096
	s_waitcnt lgkmcnt(14)
	v_mfma_f32_32x32x16_bf16 v[50:65], v[94:97], v[98:101], v[50:65]
	ds_read_b64_tr_b16 v[164:165], v252 offset:17600
	ds_read_b64_tr_b16 v[166:167], v252 offset:20160
	s_waitcnt lgkmcnt(14)
	v_mfma_f32_32x32x16_bf16 v[34:49], v[106:109], v[102:105], v[34:49]
	ds_read_b64_tr_b16 v[168:169], v252 offset:22656
	ds_read_b64_tr_b16 v[170:171], v252 offset:25216
	s_waitcnt lgkmcnt(14)
	v_mfma_f32_32x32x16_bf16 v[50:65], v[110:113], v[102:105], v[50:65]
	ds_read_b64_tr_b16 v[172:173], v252 offset:22720
	ds_read_b64_tr_b16 v[174:175], v252 offset:25280
	s_waitcnt lgkmcnt(14)
	v_mfma_f32_32x32x16_bf16 v[34:49], v[240:243], v[82:85], v[34:49]
	ds_read_b64_tr_b16 v[176:177], v252 offset:27776
	ds_read_b64_tr_b16 v[178:179], v252 offset:30336
	s_waitcnt lgkmcnt(14)
	v_mfma_f32_32x32x16_bf16 v[50:65], v[148:151], v[82:85], v[50:65]
	ds_read_b64_tr_b16 v[90:91], v252 offset:27840
	ds_read_b64_tr_b16 v[92:93], v252 offset:30400
	s_waitcnt lgkmcnt(14)
	v_mfma_f32_32x32x16_bf16 v[50:65], v[152:155], v[86:89], v[50:65]
	ds_read_b64_tr_b16 v[94:95], v252 offset:32896
	ds_read_b64_tr_b16 v[96:97], v252 offset:35456
	s_waitcnt lgkmcnt(14)
	v_mfma_f32_32x32x16_bf16 v[34:49], v[156:159], v[86:89], v[34:49]
	ds_read_b64_tr_b16 v[106:107], v252 offset:32960
	ds_read_b64_tr_b16 v[108:109], v252 offset:35520
	s_waitcnt lgkmcnt(14)
	v_mfma_f32_32x32x16_bf16 v[18:33], v[160:163], v[98:101], v[18:33]
	ds_read_b128 v[240:243], v234
	s_waitcnt lgkmcnt(13)
	v_mfma_f32_32x32x16_bf16 v[2:17], v[164:167], v[98:101], v[2:17]
	ds_read_b128 v[148:151], v234 offset:8704
	s_waitcnt lgkmcnt(12)
	v_mfma_f32_32x32x16_bf16 v[18:33], v[168:171], v[102:105], v[18:33]
	ds_read_b128 v[152:155], v234 offset:32
	s_waitcnt lgkmcnt(11)
	v_mfma_f32_32x32x16_bf16 v[2:17], v[172:175], v[102:105], v[2:17]
	ds_read_b128 v[156:159], v234 offset:8736
	s_waitcnt lgkmcnt(10)
; __device__ __forceinline__ s16x4 vtr(ldsp p) { return __builtin_bit_cast(s16x4, __builtin_amdgcn_ds_read_tr16_b64_v4i16((LAS v4i16_t*)p)); }
; template <bool DIFF>
; __device__ __forceinline__ void attn_unit(const AttnP& A, int b, int h, int qi, ldsp lds) {
;     ...
;             for (int t = 0; t < 2; ++t)
; #pragma unroll
;                 for (int j = 0; j < 4; ++j) {
;                     const bf16x8 vf = (bf16x8){vlo[t * 4 + j][0], vlo[t * 4 + j][1], vlo[t * 4 + j][2], vlo[t * 4 + j][3], vhi[t * 4 + j][0], vhi[t * 4 + j][1], vhi[t * 4 + j][2], vhi[t * 4 + j][3]};
;                     o[t] = __builtin_amdgcn_mfma_f32_32x32x16_bf16(vf, pw[j], o[t], 0, 0, 0);
;                 }
;             if (DIFF) {
; #pragma unroll
;                 for (int t = 2; t < NTD; ++t)
; #pragma unroll
;                     for (int j = 0; j < 4; ++j) { vlo[(t - 2) * 4 + j] = vtr(Vb + trb + (16 * j) * VP + t * 64); vhi[(t - 2) * 4 + j] = vtr(Vb + trb + (16 * j + 8) * VP + t * 64); }
;                 __builtin_amdgcn_sched_barrier(0);
; #pragma unroll
;                 for (int t = 2; t < NTD; ++t)
; #pragma unroll
;                     for (int j = 0; j < 4; ++j) {
;                         const int i = (t - 2) * 4 + j;
;                         const bf16x8 vf = (bf16x8){vlo[i][0], vlo[i][1], vlo[i][2], vlo[i][3], vhi[i][0], vhi[i][1], vhi[i][2], vhi[i][3]};
;                         o[t] = __builtin_amdgcn_mfma_f32_32x32x16_bf16(vf, pw[j], o[t], 0, 0, 0);
;                     }
;             }
;             __builtin_amdgcn_s_setprio(0);
;         }
;         if (kt + 1 < nt) STORE_TILE((kt + 1) & 1);
;         __syncthreads();
	v_mfma_f32_32x32x16_bf16 v[18:33], v[176:179], v[82:85], v[18:33]
	ds_read_b128 v[160:163], v234 offset:64
	s_waitcnt lgkmcnt(9)
	v_mfma_f32_32x32x16_bf16 v[2:17], v[90:93], v[82:85], v[2:17]
	ds_read_b128 v[164:167], v234 offset:8768
	s_waitcnt lgkmcnt(8)
	v_mfma_f32_32x32x16_bf16 v[18:33], v[94:97], v[86:89], v[18:33]
	ds_read_b128 v[168:171], v234 offset:96
	s_waitcnt lgkmcnt(7)
	v_mfma_f32_32x32x16_bf16 v[2:17], v[106:109], v[86:89], v[2:17]
	ds_read_b128 v[172:175], v234 offset:8800
	s_waitcnt lgkmcnt(7)
	v_mfma_f32_32x32x16_bf16 v[98:113], v[240:243], v[116:119], v[66:81]
	s_waitcnt lgkmcnt(6)
	v_mfma_f32_32x32x16_bf16 v[82:97], v[148:151], v[116:119], v[66:81]
	s_waitcnt lgkmcnt(5)
	v_mfma_f32_32x32x16_bf16 v[98:113], v[152:155], v[120:123], v[98:113]
	s_waitcnt lgkmcnt(4)
	v_mfma_f32_32x32x16_bf16 v[82:97], v[156:159], v[120:123], v[82:97]
	s_waitcnt lgkmcnt(3)
	v_mfma_f32_32x32x16_bf16 v[98:113], v[160:163], v[124:127], v[98:113]
	s_waitcnt lgkmcnt(2)
	v_mfma_f32_32x32x16_bf16 v[82:97], v[164:167], v[124:127], v[82:97]
	s_waitcnt lgkmcnt(1)
	v_mfma_f32_32x32x16_bf16 v[98:113], v[168:171], v[128:131], v[98:113]
	s_waitcnt lgkmcnt(0)
	v_mfma_f32_32x32x16_bf16 v[82:97], v[172:175], v[128:131], v[82:97]
	s_setprio 0
	s_waitcnt vmcnt(0)
	ds_write_b128 v226, v[132:135] offset:38144
	ds_write_b128 v228, v[140:143] offset:38144
	ds_write_b128 v227, v[136:139] offset:17408
	ds_write_b128 v229, v[144:147] offset:17408
	global_load_dwordx4 v[136:139], v[196:197], off offset:2048
	global_load_dwordx4 v[144:147], v[198:199], off offset:2048
	v_lshl_add_u64 v[196:197], v[196:197], 0, s[26:27]
	v_lshl_add_u64 v[198:199], v[198:199], 0, s[26:27]
	global_load_dwordx4 v[132:135], v[196:197], off offset:1024
	global_load_dwordx4 v[140:143], v[198:199], off offset:1024
	s_waitcnt lgkmcnt(0)
	s_barrier
	s_add_i32 s75, s75, 1
	s_add_i32 s74, s74, 64
	s_cmp_gt_i32 s75, s23
	s_cbranch_scc1 .Ldb_gen
.Ldb_s_odd:
	v_exp_f32_e32 v148, v98
	v_exp_f32_e32 v164, v82
	v_exp_f32_e32 v149, v99
	v_exp_f32_e32 v165, v83
	v_add_f32_e32 v237, 0, v148
	v_add_f32_e32 v238, 0, v164
	v_exp_f32_e32 v150, v100
	v_exp_f32_e32 v166, v84
	v_add_f32_e32 v237, v149, v237
	v_add_f32_e32 v238, v165, v238
	v_exp_f32_e32 v151, v101
	v_exp_f32_e32 v167, v85
	v_add_f32_e32 v237, v150, v237
	v_add_f32_e32 v238, v166, v238
	v_exp_f32_e32 v152, v102
	v_exp_f32_e32 v168, v86
	v_add_f32_e32 v237, v151, v237
	v_add_f32_e32 v238, v167, v238
	v_exp_f32_e32 v153, v103
	v_exp_f32_e32 v169, v87
	v_add_f32_e32 v237, v152, v237
	v_add_f32_e32 v238, v168, v238
	v_exp_f32_e32 v154, v104
	v_exp_f32_e32 v170, v88
	v_add_f32_e32 v237, v153, v237
	v_add_f32_e32 v238, v169, v238
	v_exp_f32_e32 v155, v105
	v_exp_f32_e32 v171, v89
	v_add_f32_e32 v237, v154, v237
	v_add_f32_e32 v238, v170, v238
	v_exp_f32_e32 v156, v106
	v_exp_f32_e32 v172, v90
	v_add_f32_e32 v237, v155, v237
	v_add_f32_e32 v238, v171, v238
	v_exp_f32_e32 v157, v107
	v_exp_f32_e32 v173, v91
	v_add_f32_e32 v237, v156, v237
	v_add_f32_e32 v238, v172, v238
	v_exp_f32_e32 v158, v108
	v_exp_f32_e32 v174, v92
	v_add_f32_e32 v237, v157, v237
	v_add_f32_e32 v238, v173, v238
	v_exp_f32_e32 v159, v109
	v_exp_f32_e32 v175, v93
	v_add_f32_e32 v237, v158, v237
	v_add_f32_e32 v238, v174, v238
	v_exp_f32_e32 v160, v110
	v_exp_f32_e32 v176, v94
	v_add_f32_e32 v237, v159, v237
	v_add_f32_e32 v238, v175, v238
	v_exp_f32_e32 v161, v111
	v_exp_f32_e32 v177, v95
	v_add_f32_e32 v237, v160, v237
	v_add_f32_e32 v238, v176, v238
	v_exp_f32_e32 v162, v112
	v_exp_f32_e32 v178, v96
	v_add_f32_e32 v237, v161, v237
	v_add_f32_e32 v238, v177, v238
	v_exp_f32_e32 v163, v113
	v_exp_f32_e32 v179, v97
	v_add_f32_e32 v237, v162, v237
	v_add_f32_e32 v238, v178, v238
	s_nop 0
	v_add_f32_e32 v237, v163, v237
	v_add_f32_e32 v238, v179, v238
	v_add_f32_e32 v204, v237, v238
	v_cmp_lt_f32_e32 vcc, s85, v204
	s_cbranch_vccnz .Ldb_s_slow
; __device__ __forceinline__ unsigned cvtpk(float lo, float hi) { f32x2 v = {lo, hi}; bf16x2_t b = __builtin_convertvector(v, bf16x2_t); return __builtin_bit_cast(unsigned, b); }
; template <bool DIFF>
; __device__ __forceinline__ void attn_unit(const AttnP& A, int b, int h, int qi, ldsp lds) {
;     ...
;             bf16x8 pw[4];
; #pragma unroll
;             for (int j = 0; j < 4; ++j) {
;                 u32x4 pk;
;                 if (j < 2) { const int rb = 8 * (j & 1); pk.x = cvtpk(s0[rb], s0[rb + 1]); pk.y = cvtpk(s0[rb + 2], s0[rb + 3]); pk.z = cvtpk(s0[rb + 4], s0[rb + 5]); pk.w = cvtpk(s0[rb + 6], s0[rb + 7]); }
;                 else { const int rb = 8 * (j & 1); pk.x = cvtpk(s1[rb], s1[rb + 1]); pk.y = cvtpk(s1[rb + 2], s1[rb + 3]); pk.z = cvtpk(s1[rb + 4], s1[rb + 5]); pk.w = cvtpk(s1[rb + 6], s1[rb + 7]); }
;                 pw[j] = __builtin_bit_cast(bf16x8, pk);
;             }
;             __builtin_amdgcn_sched_barrier(0);
;             __builtin_amdgcn_s_setprio(1);
; #pragma unroll
;             for (int t = 0; t < 2; ++t)
; #pragma unroll
;                 for (int j = 0; j < 4; ++j) {
;                     const bf16x8 vf = (bf16x8){vlo[t * 4 + j][0], vlo[t * 4 + j][1], vlo[t * 4 + j][2], vlo[t * 4 + j][3], vhi[t * 4 + j][0], vhi[t * 4 + j][1], vhi[t * 4 + j][2], vhi[t * 4 + j][3]};
;                     o[t] = __builtin_amdgcn_mfma_f32_32x32x16_bf16(vf, pw[j], o[t], 0, 0, 0);
;                 }
;             if (DIFF) {
; #pragma unroll
;                 for (int t = 2; t < NTD; ++t)
; #pragma unroll
;                     for (int j = 0; j < 4; ++j) { vlo[(t - 2) * 4 + j] = vtr(Vb + trb + (16 * j) * VP + t * 64); vhi[(t - 2) * 4 + j] = vtr(Vb + trb + (16 * j + 8) * VP + t * 64); }
;                 __builtin_amdgcn_sched_barrier(0);
; #pragma unroll
;                 for (int t = 2; t < NTD; ++t)
; #pragma unroll
;                     for (int j = 0; j < 4; ++j) {
;                         const int i = (t - 2) * 4 + j;
;                         const bf16x8 vf = (bf16x8){vlo[i][0], vlo[i][1], vlo[i][2], vlo[i][3], vhi[i][0], vhi[i][1], vhi[i][2], vhi[i][3]};
;                         o[t] = __builtin_amdgcn_mfma_f32_32x32x16_bf16(vf, pw[j], o[t], 0, 0, 0);
;                     }
;             }
;             __builtin_amdgcn_s_setprio(0);
;         }
;         if (kt + 1 < nt) STORE_TILE((kt + 1) & 1);
;         __syncthreads();
	ds_read_b64_tr_b16 v[90:91], v231 offset:17472
	ds_read_b64_tr_b16 v[92:93], v231 offset:20032
	ds_read_b64_tr_b16 v[94:95], v231 offset:17408
	ds_read_b64_tr_b16 v[96:97], v231 offset:19968
	ds_read_b64_tr_b16 v[106:107], v231 offset:22592
	ds_read_b64_tr_b16 v[108:109], v231 offset:25152
	ds_read_b64_tr_b16 v[110:111], v231 offset:22528
	ds_read_b64_tr_b16 v[112:113], v231 offset:25088
	ds_read_b64_tr_b16 v[240:241], v231 offset:27712
	ds_read_b64_tr_b16 v[242:243], v231 offset:30272
	v_cvt_pk_bf16_f32 v98, v148, v149
	v_cvt_pk_bf16_f32 v99, v150, v151
	v_cvt_pk_bf16_f32 v100, v152, v153
	v_cvt_pk_bf16_f32 v101, v154, v155
	v_cvt_pk_bf16_f32 v102, v156, v157
	v_cvt_pk_bf16_f32 v103, v158, v159
	v_cvt_pk_bf16_f32 v104, v160, v161
	v_cvt_pk_bf16_f32 v105, v162, v163
	v_cvt_pk_bf16_f32 v82, v164, v165
	v_cvt_pk_bf16_f32 v83, v166, v167
	v_cvt_pk_bf16_f32 v84, v168, v169
	v_cvt_pk_bf16_f32 v85, v170, v171
	v_cvt_pk_bf16_f32 v86, v172, v173
	v_cvt_pk_bf16_f32 v87, v174, v175
	v_cvt_pk_bf16_f32 v88, v176, v177
	v_cvt_pk_bf16_f32 v89, v178, v179
	v_add_f32_e32 v230, v204, v230
	ds_read_b64_tr_b16 v[148:149], v231 offset:27648
	ds_read_b64_tr_b16 v[150:151], v231 offset:30208
	ds_read_b64_tr_b16 v[152:153], v231 offset:32768
	ds_read_b64_tr_b16 v[154:155], v231 offset:35328
	ds_read_b64_tr_b16 v[156:157], v231 offset:32832
	ds_read_b64_tr_b16 v[158:159], v231 offset:35392
	s_setprio 1
	s_waitcnt lgkmcnt(14)
	v_mfma_f32_32x32x16_bf16 v[34:49], v[90:93], v[98:101], v[34:49]
	ds_read_b64_tr_b16 v[160:161], v231 offset:17536
	ds_read_b64_tr_b16 v[162:163], v231 offset:20096
	s_waitcnt lgkmcnt(14)
	v_mfma_f32_32x32x16_bf16 v[50:65], v[94:97], v[98:101], v[50:65]
	ds_read_b64_tr_b16 v[164:165], v231 offset:17600
	ds_read_b64_tr_b16 v[166:167], v231 offset:20160
	s_waitcnt lgkmcnt(14)
	v_mfma_f32_32x32x16_bf16 v[34:49], v[106:109], v[102:105], v[34:49]
	ds_read_b64_tr_b16 v[168:169], v231 offset:22656
	ds_read_b64_tr_b16 v[170:171], v231 offset:25216
	s_waitcnt lgkmcnt(14)
	v_mfma_f32_32x32x16_bf16 v[50:65], v[110:113], v[102:105], v[50:65]
	ds_read_b64_tr_b16 v[172:173], v231 offset:22720
	ds_read_b64_tr_b16 v[174:175], v231 offset:25280
	s_waitcnt lgkmcnt(14)
	v_mfma_f32_32x32x16_bf16 v[34:49], v[240:243], v[82:85], v[34:49]
	ds_read_b64_tr_b16 v[176:177], v231 offset:27776
	ds_read_b64_tr_b16 v[178:179], v231 offset:30336
	s_waitcnt lgkmcnt(14)
	v_mfma_f32_32x32x16_bf16 v[50:65], v[148:151], v[82:85], v[50:65]
	ds_read_b64_tr_b16 v[90:91], v231 offset:27840
	ds_read_b64_tr_b16 v[92:93], v231 offset:30400
	s_waitcnt lgkmcnt(14)
	v_mfma_f32_32x32x16_bf16 v[50:65], v[152:155], v[86:89], v[50:65]
	ds_read_b64_tr_b16 v[94:95], v231 offset:32896
	ds_read_b64_tr_b16 v[96:97], v231 offset:35456
	s_waitcnt lgkmcnt(14)
	v_mfma_f32_32x32x16_bf16 v[34:49], v[156:159], v[86:89], v[34:49]
	ds_read_b64_tr_b16 v[106:107], v231 offset:32960
	ds_read_b64_tr_b16 v[108:109], v231 offset:35520
	s_waitcnt lgkmcnt(14)
	v_mfma_f32_32x32x16_bf16 v[18:33], v[160:163], v[98:101], v[18:33]
	ds_read_b128 v[240:243], v234 offset:38144
	s_waitcnt lgkmcnt(13)
	v_mfma_f32_32x32x16_bf16 v[2:17], v[164:167], v[98:101], v[2:17]
	ds_read_b128 v[148:151], v234 offset:46848
	s_waitcnt lgkmcnt(12)
	v_mfma_f32_32x32x16_bf16 v[18:33], v[168:171], v[102:105], v[18:33]
	ds_read_b128 v[152:155], v234 offset:38176
	s_waitcnt lgkmcnt(11)
	v_mfma_f32_32x32x16_bf16 v[2:17], v[172:175], v[102:105], v[2:17]
	ds_read_b128 v[156:159], v234 offset:46880
	s_waitcnt lgkmcnt(10)
	v_mfma_f32_32x32x16_bf16 v[18:33], v[176:179], v[82:85], v[18:33]
	ds_read_b128 v[160:163], v234 offset:38208
	s_waitcnt lgkmcnt(9)
	v_mfma_f32_32x32x16_bf16 v[2:17], v[90:93], v[82:85], v[2:17]
	ds_read_b128 v[164:167], v234 offset:46912
	s_waitcnt lgkmcnt(8)
	v_mfma_f32_32x32x16_bf16 v[18:33], v[94:97], v[86:89], v[18:33]
	ds_read_b128 v[168:171], v234 offset:38240
	s_waitcnt lgkmcnt(7)
	v_mfma_f32_32x32x16_bf16 v[2:17], v[106:109], v[86:89], v[2:17]
	ds_read_b128 v[172:175], v234 offset:46944
	s_waitcnt lgkmcnt(7)
	v_mfma_f32_32x32x16_bf16 v[98:113], v[240:243], v[116:119], v[66:81]
	s_waitcnt lgkmcnt(6)
	v_mfma_f32_32x32x16_bf16 v[82:97], v[148:151], v[116:119], v[66:81]
	s_waitcnt lgkmcnt(5)
	v_mfma_f32_32x32x16_bf16 v[98:113], v[152:155], v[120:123], v[98:113]
	s_waitcnt lgkmcnt(4)
	v_mfma_f32_32x32x16_bf16 v[82:97], v[156:159], v[120:123], v[82:97]
	s_waitcnt lgkmcnt(3)
	v_mfma_f32_32x32x16_bf16 v[98:113], v[160:163], v[124:127], v[98:113]
	s_waitcnt lgkmcnt(2)
	v_mfma_f32_32x32x16_bf16 v[82:97], v[164:167], v[124:127], v[82:97]
	s_waitcnt lgkmcnt(1)
	v_mfma_f32_32x32x16_bf16 v[98:113], v[168:171], v[128:131], v[98:113]
	s_waitcnt lgkmcnt(0)
	v_mfma_f32_32x32x16_bf16 v[82:97], v[172:175], v[128:131], v[82:97]
	s_setprio 0
	s_waitcnt vmcnt(0)
	ds_write_b128 v226, v[132:135]
	ds_write_b128 v228, v[140:143]
	ds_write_b128 v227, v[136:139] offset:55552
	ds_write_b128 v229, v[144:147] offset:55552
	global_load_dwordx4 v[136:139], v[196:197], off offset:2048
	global_load_dwordx4 v[144:147], v[198:199], off offset:2048
	v_lshl_add_u64 v[196:197], v[196:197], 0, s[26:27]
	v_lshl_add_u64 v[198:199], v[198:199], 0, s[26:27]
	global_load_dwordx4 v[132:135], v[196:197], off offset:1024
	global_load_dwordx4 v[140:143], v[198:199], off offset:1024
	s_waitcnt lgkmcnt(0)
	s_barrier
	s_add_i32 s75, s75, 1
	s_add_i32 s74, s74, 64
	s_cmp_le_i32 s75, s23
	s_cbranch_scc1 .Ldb_s_even
